# work queue: next item index fetched at start of current item (first at phase entry), on top of staggered attention
# speedup vs baseline: 1.0132x; 1.0092x over previous
; #define LAS __attribute__((address_space(3)))
; #define OPQV(x) asm volatile("" : "+v"(x))
; DEV unsigned cvt_pk_bf16(float lo, float hi) { unsigned r; asm volatile("v_cvt_pk_bf16_f32 %0, %1, %2" : "=v"(r) : "v"(lo), "v"(hi)); return r; }
; DEV void attn_item(LAS unsigned char* lds, const bf16_t* P, const bf16_t* QB, const bf16_t* KV, const bf16_t* KC, const bf16_t* VC, const float* rel_bias, bf16_t* OB, int b, int g, int qt) {
;     ...
; #pragma unroll
;     for (int hh = 0; hh < 2; ++hh)
; #pragma unroll
;         for (int dt = 0; dt < 4; ++dt) { u32x2 w; w.x = cvt_pk_bf16(F[hh][dt][0], F[hh][dt][1]); w.y = cvt_pk_bf16(F[hh][dt][2], F[hh][dt][3]);
;             *(u32x2*)(OB + tok * 1024 + (g * 4 + hp * 2 + hh) * 64 + dt * 16 + g4 * 4) = w; }
; DEV void phase_mix(LAS unsigned char* lds, const bf16_t* P, const bf16_t* QB, const bf16_t* KV, const bf16_t* KC, const bf16_t* VC, const float* rel_bias, bf16_t* OB,
;                    const bf16_t* VN, const float* sgu_w, const float* sgu_b, bf16_t* OC, int* ctr) {
;     int tid = threadIdx.x; OPQV(tid);
;     LAS int* BK = (LAS int*)(lds + AT_BK);
;     if (tid < 129) { int bk; if (tid < 16) bk = tid; else { const float lr = log2f((float)tid * (1.f / 16.f)) * (1.f / 3.f); bk = 16 + (int)(lr * 16.f); if (bk > 31) bk = 31; } BK[tid] = bk; }
;     *(LAS float*)(lds + AT_RB + tid * 4) = rel_bias[tid];
;     __syncthreads();
;     for (;;) {
;         if (tid == 0) *(LAS int*)(lds + AT_NEXT) = atomicAdd(ctr, 1);
.LBB0_156:
	s_or_b64 exec, exec, s[4:5]
	s_load_dwordx2 s[4:5], s[0:1], 0x8
	v_ashrrev_i32_e32 v3, 31, v2
	s_add_u32 s78, s62, 0x26988000
	s_addc_u32 s79, s63, 0
	s_add_u32 s70, s62, 0x20989000
	s_waitcnt lgkmcnt(0)
	v_lshl_add_u64 v[4:5], v[2:3], 2, s[4:5]
	global_load_dword v0, v[4:5], off
	s_addc_u32 s8, s63, 0
	s_ashr_i32 s15, s14, 31
	s_lshl_b64 s[4:5], s[14:15], 19
	s_add_u32 s80, s40, s4
	s_addc_u32 s81, s41, s5
	s_lshl_b64 s[4:5], s[14:15], 12
	s_add_u32 s82, s42, s4
	s_addc_u32 s83, s43, s5
	s_lshl_b32 s4, s14, 6
	s_ashr_i32 s5, s4, 31
	s_lshl_b64 s[4:5], s[4:5], 2
	s_add_u32 s4, s62, s4
	s_addc_u32 s5, s63, s5
	s_add_u32 s84, s4, 0x20988000
	s_addc_u32 s85, s5, 0
	s_add_u32 s86, s62, 0x1c988000
	s_addc_u32 s87, s63, 0
	v_lshl_add_u32 v3, v2, 2, 0
	s_add_u32 s88, s62, 0x1e988000
	v_add_u32_e32 v3, 0x13d00, v3
	s_addc_u32 s89, s63, 0
	v_cmp_eq_u32_e64 s[40:41], 0, v2
	s_waitcnt vmcnt(0)
	ds_write_b32 v3, v0
	s_waitcnt lgkmcnt(0)
	s_barrier
	s_and_saveexec_b64 s[6:7], s[40:41]
	s_cbranch_execz .Lwq_skip_e
	v_mov_b32_e32 v214, 1
	global_atomic_add v214, v1, v214, s[84:85] sc0
.Lwq_skip_e:
	s_or_b64 exec, exec, s[6:7]
	s_branch .LBB0_160
.LBB0_157:
	v_lshl_add_u64 v[2:3], s[86:87], 0, v[96:97]
	v_lshlrev_b32_e32 v0, 1, v138
	v_lshl_add_u64 v[2:3], v[2:3], 0, v[0:1]
	v_lshlrev_b32_e32 v0, 1, v140
	v_lshl_add_u64 v[2:3], v[2:3], 0, v[0:1]
	v_cvt_pk_bf16_f32 v4, v134, v135
	v_cvt_pk_bf16_f32 v5, v130, v131
	global_store_dwordx2 v[2:3], v[4:5], off
	v_cvt_pk_bf16_f32 v4, v132, v133
	v_cvt_pk_bf16_f32 v5, v128, v129
	global_store_dwordx2 v[2:3], v[4:5], off offset:32
	v_cvt_pk_bf16_f32 v4, v124, v125
	v_cvt_pk_bf16_f32 v5, v120, v121
	global_store_dwordx2 v[2:3], v[4:5], off offset:64
	v_cvt_pk_bf16_f32 v4, v122, v123
	v_cvt_pk_bf16_f32 v5, v118, v119
	global_store_dwordx2 v[2:3], v[4:5], off offset:96
	v_cvt_pk_bf16_f32 v4, v116, v117
	v_cvt_pk_bf16_f32 v5, v114, v115
	global_store_dwordx2 v[2:3], v[4:5], off offset:128
	v_cvt_pk_bf16_f32 v4, v112, v113
	v_cvt_pk_bf16_f32 v5, v110, v111
	v_readlane_b32 s90, v254, 53
	v_readlane_b32 s92, v254, 55
	global_store_dwordx2 v[2:3], v[4:5], off offset:160
	v_cvt_pk_bf16_f32 v4, v108, v109
	v_cvt_pk_bf16_f32 v5, v104, v105
	v_readlane_b32 s91, v254, 54
	v_readlane_b32 s93, v254, 56
	s_movk_i32 s94, 0x80
	v_readlane_b32 s95, v254, 58
	s_movk_i32 s96, 0x204
	s_movk_i32 s97, 0xb80
	global_store_dwordx2 v[2:3], v[4:5], off offset:192
	v_cvt_pk_bf16_f32 v4, v106, v107
	v_cvt_pk_bf16_f32 v5, v102, v103
	global_store_dwordx2 v[2:3], v[4:5], off offset:224

; #define LAS __attribute__((address_space(3)))
; DEV void phase_mix(LAS unsigned char* lds, const bf16_t* P, const bf16_t* QB, const bf16_t* KV, const bf16_t* KC, const bf16_t* VC, const float* rel_bias, bf16_t* OB,
;                    const bf16_t* VN, const float* sgu_w, const float* sgu_b, bf16_t* OC, int* ctr) {
;     ...
;     for (;;) {
;         if (tid == 0) *(LAS int*)(lds + AT_NEXT) = atomicAdd(ctr, 1);
;         __syncthreads();
;         const int i = *(const LAS int*)(lds + AT_NEXT);
;         __syncthreads();
;         if (i >= 2048) break;
;         if (i < 1024) attn_item(lds, P, QB, KV, KC, VC, rel_bias, OB, (i & 31) >> 2, i & 3, 31 - (i >> 5));
.LBB0_160:
	s_and_saveexec_b64 s[4:5], s[40:41]
	s_cbranch_execz .LBB0_164
	v_mov_b32_e32 v2, s95
	s_waitcnt vmcnt(0)
	ds_write_b32 v2, v214
.LBB0_164:
	s_or_b64 exec, exec, s[4:5]
	v_mov_b32_e32 v0, s95
	s_waitcnt lgkmcnt(0)
	s_barrier
	ds_read_b32 v0, v0
	s_movk_i32 s4, 0x7ff
	s_waitcnt lgkmcnt(0)
	s_barrier
	v_cmp_lt_i32_e32 vcc, s4, v0
	v_readfirstlane_b32 s43, v0
	s_mov_b64 s[4:5], -1
	s_cbranch_vccnz .LBB0_159
	s_and_saveexec_b64 s[6:7], s[40:41]
	s_cbranch_execz .Lwq_skip_i
	v_mov_b32_e32 v214, 1
	global_atomic_add v214, v1, v214, s[84:85] sc0
